# barrier leader issues the XGEN release atomic before its own L1 invalidate (all 13 instances)
# baseline (speedup 1.0000x reference)
; __device__ __forceinline__ unsigned xb_ld(unsigned* p)              { return __hip_atomic_load(p, __ATOMIC_RELAXED, __HIP_MEMORY_SCOPE_AGENT); }
; __device__ __forceinline__ unsigned xb_add(unsigned* p, unsigned v) { return __hip_atomic_fetch_add(p, v, __ATOMIC_RELAXED, __HIP_MEMORY_SCOPE_AGENT); }
; #define XB_SPIN(cond, bar) do { unsigned _sp = 0; while (cond) { __builtin_amdgcn_s_sleep(1); \
;     if ((++_sp & 255u) == 0u) { if (xb_ld(&(bar)[XB_TMO])) break; if (_sp > XB_SPIN_CAP) { atomicAdd(&(bar)[XB_TMO], 1u); break; } } } } while (0)
; __device__ __forceinline__ void xcd_barrier(const XcdBarrier& b) {
;     ...
;             if (og + 1u == (tg + 1u) * nx) xb_add(&bar[XB_TOPGEN], 1u);
;             else XB_SPIN(xb_ld(&bar[XB_TOPGEN]) == tg, bar);
;             __builtin_amdgcn_fence(__ATOMIC_ACQUIRE, "agent");
;             xb_add(&bar[XB_XGEN(b.x)], 1u);
;             asm volatile("s_waitcnt vmcnt(0)" ::: "memory");
.Lgb0_137:
	s_or_b64 exec, exec, s[6:7]
	s_mov_b64 s[6:7], exec
	v_mbcnt_lo_u32_b32 v0, s6, 0
	v_mbcnt_hi_u32_b32 v0, s7, v0
	v_cmp_eq_u32_e32 vcc, 0, v0
	s_waitcnt vmcnt(0)
	s_and_saveexec_b64 s[10:11], vcc
	s_cbranch_execz .Lgb0_139
	s_bcnt1_i32_b64 s6, s[6:7]
	v_mov_b32_e32 v0, 0x2000
	v_mov_b32_e32 v1, s6
	global_atomic_add v0, v1, s[4:5] offset:1024
.Lgb0_139:
	s_or_b64 exec, exec, s[10:11]
	buffer_inv sc1
	s_waitcnt vmcnt(0)

; __device__ __forceinline__ unsigned xb_ld(unsigned* p)              { return __hip_atomic_load(p, __ATOMIC_RELAXED, __HIP_MEMORY_SCOPE_AGENT); }
; __device__ __forceinline__ unsigned xb_add(unsigned* p, unsigned v) { return __hip_atomic_fetch_add(p, v, __ATOMIC_RELAXED, __HIP_MEMORY_SCOPE_AGENT); }
; #define XB_SPIN(cond, bar) do { unsigned _sp = 0; while (cond) { __builtin_amdgcn_s_sleep(1); \
;     if ((++_sp & 255u) == 0u) { if (xb_ld(&(bar)[XB_TMO])) break; if (_sp > XB_SPIN_CAP) { atomicAdd(&(bar)[XB_TMO], 1u); break; } } } } while (0)
; __device__ __forceinline__ void xcd_barrier(const XcdBarrier& b) {
;     ...
;             if (og + 1u == (tg + 1u) * nx) xb_add(&bar[XB_TOPGEN], 1u);
;             else XB_SPIN(xb_ld(&bar[XB_TOPGEN]) == tg, bar);
;             __builtin_amdgcn_fence(__ATOMIC_ACQUIRE, "agent");
;             xb_add(&bar[XB_XGEN(b.x)], 1u);
;             asm volatile("s_waitcnt vmcnt(0)" ::: "memory");
.LBB0_207:
	s_or_b64 exec, exec, s[10:11]
	s_mov_b64 s[10:11], exec
	v_mbcnt_lo_u32_b32 v0, s10, 0
	v_mbcnt_hi_u32_b32 v0, s11, v0
	v_cmp_eq_u32_e32 vcc, 0, v0
	s_waitcnt vmcnt(0)
	s_and_saveexec_b64 s[16:17], vcc
	s_cbranch_execz .LBB0_209
	s_bcnt1_i32_b64 s10, s[10:11]
	v_mov_b32_e32 v0, 0x2000
	v_mov_b32_e32 v1, s10
	global_atomic_add v0, v1, s[6:7] offset:1024
.LBB0_209:
	s_or_b64 exec, exec, s[16:17]
	buffer_inv sc1
	s_waitcnt vmcnt(0)

; __device__ __forceinline__ unsigned xb_ld(unsigned* p)              { return __hip_atomic_load(p, __ATOMIC_RELAXED, __HIP_MEMORY_SCOPE_AGENT); }
; __device__ __forceinline__ unsigned xb_add(unsigned* p, unsigned v) { return __hip_atomic_fetch_add(p, v, __ATOMIC_RELAXED, __HIP_MEMORY_SCOPE_AGENT); }
; #define XB_SPIN(cond, bar) do { unsigned _sp = 0; while (cond) { __builtin_amdgcn_s_sleep(1); \
;     if ((++_sp & 255u) == 0u) { if (xb_ld(&(bar)[XB_TMO])) break; if (_sp > XB_SPIN_CAP) { atomicAdd(&(bar)[XB_TMO], 1u); break; } } } } while (0)
; __device__ __forceinline__ void xcd_barrier(const XcdBarrier& b) {
;     ...
;             if (og + 1u == (tg + 1u) * nx) xb_add(&bar[XB_TOPGEN], 1u);
;             else XB_SPIN(xb_ld(&bar[XB_TOPGEN]) == tg, bar);
;             __builtin_amdgcn_fence(__ATOMIC_ACQUIRE, "agent");
;             xb_add(&bar[XB_XGEN(b.x)], 1u);
;             asm volatile("s_waitcnt vmcnt(0)" ::: "memory");
.LBB0_360:
	s_or_b64 exec, exec, s[6:7]
	s_mov_b64 s[6:7], exec
	v_mbcnt_lo_u32_b32 v0, s6, 0
	v_mbcnt_hi_u32_b32 v0, s7, v0
	v_cmp_eq_u32_e32 vcc, 0, v0
	s_waitcnt vmcnt(0)
	s_and_saveexec_b64 s[8:9], vcc
	s_cbranch_execz .LBB0_362
	s_bcnt1_i32_b64 s6, s[6:7]
	v_mov_b32_e32 v0, 0x2000
	v_mov_b32_e32 v1, s6
	global_atomic_add v0, v1, s[4:5] offset:1024
.LBB0_362:
	s_or_b64 exec, exec, s[8:9]
	buffer_inv sc1
	s_waitcnt vmcnt(0)

; __device__ __forceinline__ unsigned xb_ld(unsigned* p)              { return __hip_atomic_load(p, __ATOMIC_RELAXED, __HIP_MEMORY_SCOPE_AGENT); }
; __device__ __forceinline__ unsigned xb_add(unsigned* p, unsigned v) { return __hip_atomic_fetch_add(p, v, __ATOMIC_RELAXED, __HIP_MEMORY_SCOPE_AGENT); }
; #define XB_SPIN(cond, bar) do { unsigned _sp = 0; while (cond) { __builtin_amdgcn_s_sleep(1); \
;     if ((++_sp & 255u) == 0u) { if (xb_ld(&(bar)[XB_TMO])) break; if (_sp > XB_SPIN_CAP) { atomicAdd(&(bar)[XB_TMO], 1u); break; } } } } while (0)
; __device__ __forceinline__ void xcd_barrier(const XcdBarrier& b) {
;     ...
;             if (og + 1u == (tg + 1u) * nx) xb_add(&bar[XB_TOPGEN], 1u);
;             else XB_SPIN(xb_ld(&bar[XB_TOPGEN]) == tg, bar);
;             __builtin_amdgcn_fence(__ATOMIC_ACQUIRE, "agent");
;             xb_add(&bar[XB_XGEN(b.x)], 1u);
;             asm volatile("s_waitcnt vmcnt(0)" ::: "memory");
.LBB0_995:
	s_or_b64 exec, exec, s[8:9]
	s_mov_b64 s[8:9], exec
	v_mbcnt_lo_u32_b32 v0, s8, 0
	v_mbcnt_hi_u32_b32 v0, s9, v0
	v_cmp_eq_u32_e32 vcc, 0, v0
	s_waitcnt vmcnt(0)
	s_and_saveexec_b64 s[10:11], vcc
	s_cbranch_execz .LBB0_997
	s_bcnt1_i32_b64 s8, s[8:9]
	v_mov_b32_e32 v0, 0x2000
	v_mov_b32_e32 v1, s8
	global_atomic_add v0, v1, s[4:5] offset:1024

; __device__ __forceinline__ unsigned xb_ld(unsigned* p)              { return __hip_atomic_load(p, __ATOMIC_RELAXED, __HIP_MEMORY_SCOPE_AGENT); }
; __device__ __forceinline__ unsigned xb_add(unsigned* p, unsigned v) { return __hip_atomic_fetch_add(p, v, __ATOMIC_RELAXED, __HIP_MEMORY_SCOPE_AGENT); }
; #define XB_SPIN(cond, bar) do { unsigned _sp = 0; while (cond) { __builtin_amdgcn_s_sleep(1); \
;     if ((++_sp & 255u) == 0u) { if (xb_ld(&(bar)[XB_TMO])) break; if (_sp > XB_SPIN_CAP) { atomicAdd(&(bar)[XB_TMO], 1u); break; } } } } while (0)
; __device__ __forceinline__ void xcd_barrier(const XcdBarrier& b) {
;     ...
;             if (og + 1u == (tg + 1u) * nx) xb_add(&bar[XB_TOPGEN], 1u);
;             else XB_SPIN(xb_ld(&bar[XB_TOPGEN]) == tg, bar);
;             __builtin_amdgcn_fence(__ATOMIC_ACQUIRE, "agent");
;             xb_add(&bar[XB_XGEN(b.x)], 1u);
;             asm volatile("s_waitcnt vmcnt(0)" ::: "memory");
.LBB0_1227:
	s_or_b64 exec, exec, s[8:9]
	s_mov_b64 s[8:9], exec
	v_mbcnt_lo_u32_b32 v0, s8, 0
	v_mbcnt_hi_u32_b32 v0, s9, v0
	v_cmp_eq_u32_e32 vcc, 0, v0
	s_waitcnt vmcnt(0)
	s_and_saveexec_b64 s[10:11], vcc
	s_cbranch_execz .LBB0_1229
	s_bcnt1_i32_b64 s8, s[8:9]
	v_mov_b32_e32 v0, 0x2000
	v_mov_b32_e32 v1, s8
	global_atomic_add v0, v1, s[6:7] offset:1024

; __device__ __forceinline__ unsigned xb_ld(unsigned* p)              { return __hip_atomic_load(p, __ATOMIC_RELAXED, __HIP_MEMORY_SCOPE_AGENT); }
; __device__ __forceinline__ unsigned xb_add(unsigned* p, unsigned v) { return __hip_atomic_fetch_add(p, v, __ATOMIC_RELAXED, __HIP_MEMORY_SCOPE_AGENT); }
; #define XB_SPIN(cond, bar) do { unsigned _sp = 0; while (cond) { __builtin_amdgcn_s_sleep(1); \
;     if ((++_sp & 255u) == 0u) { if (xb_ld(&(bar)[XB_TMO])) break; if (_sp > XB_SPIN_CAP) { atomicAdd(&(bar)[XB_TMO], 1u); break; } } } } while (0)
; __device__ __forceinline__ void xcd_barrier(const XcdBarrier& b) {
;     ...
;             if (og + 1u == (tg + 1u) * nx) xb_add(&bar[XB_TOPGEN], 1u);
;             else XB_SPIN(xb_ld(&bar[XB_TOPGEN]) == tg, bar);
;             __builtin_amdgcn_fence(__ATOMIC_ACQUIRE, "agent");
;             xb_add(&bar[XB_XGEN(b.x)], 1u);
;             asm volatile("s_waitcnt vmcnt(0)" ::: "memory");
.LBB0_1368:
	s_or_b64 exec, exec, s[6:7]
	s_mov_b64 s[6:7], exec
	v_mbcnt_lo_u32_b32 v0, s6, 0
	v_mbcnt_hi_u32_b32 v0, s7, v0
	v_cmp_eq_u32_e32 vcc, 0, v0
	s_waitcnt vmcnt(0)
	s_and_saveexec_b64 s[8:9], vcc
	s_cbranch_execz .LBB0_1370
	s_bcnt1_i32_b64 s6, s[6:7]
	v_mov_b32_e32 v0, 0x2000
	v_mov_b32_e32 v1, s6
	global_atomic_add v0, v1, s[2:3] offset:1024
